# previous + retention scan: both sets of 16 lane-masked decay-weight blocks made branch-free with batched LDS table reads
# speedup vs baseline: 1.0739x; 1.0143x over previous
; DI int crow(int r, int hi) { return (r & 3) + 8 * (r >> 2) + 4 * hi; }
; template <bool ML>
; DI void scan_block(const Params& p, int sitem, char* smem) {
;     ...
;         const float sBx = tbx ? sB1 : sB0;
; #pragma unroll
;         for (int r = 0; r < 16; ++r) {
;           const int sl = crow(r, hi);
;           const bool valid = dir == 0 ? sl <= l32 : sl >= l32;
;           float w0, wx;
;           if (ML) { w0 = __expf(sB0 + wsm[64 + sl]); wx = __expf(sBx + wsm[64 + sbx * 32 + sl]); }
;           else { w0 = sB0 * wsm[64 + sl]; wx = sBx * wsm[64 + sbx * 32 + sl]; }
;           sd0[r] = valid ? sd0[r] * w0 : 0.f; sx[r] *= wx;
.LBB0_1464:
	v_add_u32_e32 v205, s46, v243
	v_add_u32_e32 v206, s47, v243
	ds_read_b128 v[244:247], v243 offset:17408
	ds_read_b128 v[248:251], v243
	ds_read_b128 v[210:213], v205 offset:17408
	ds_read_b128 v[216:219], v206
	s_waitcnt lgkmcnt(2)
	v_mfma_f32_32x32x16_bf16 v[112:127], v[244:247], v[248:251], v[112:127]
	ds_read_b128 v[244:247], v243 offset:17440
	ds_read_b128 v[248:251], v243 offset:32
	s_waitcnt lgkmcnt(2)
	v_mfma_f32_32x32x16_bf16 v[96:111], v[210:213], v[216:219], v[96:111]
	ds_read_b128 v[210:213], v205 offset:17440
	ds_read_b128 v[216:219], v206 offset:32
	s_waitcnt lgkmcnt(2)
	v_mfma_f32_32x32x16_bf16 v[112:127], v[244:247], v[248:251], v[112:127]
	ds_read_b128 v[244:247], v243 offset:17472
	ds_read_b128 v[248:251], v243 offset:64
	s_waitcnt lgkmcnt(2)
	v_mfma_f32_32x32x16_bf16 v[96:111], v[210:213], v[216:219], v[96:111]
	ds_read_b128 v[210:213], v205 offset:17472
	ds_read_b128 v[216:219], v206 offset:64
	s_waitcnt lgkmcnt(2)
	v_mfma_f32_32x32x16_bf16 v[112:127], v[244:247], v[248:251], v[112:127]
	ds_read_b128 v[244:247], v243 offset:17504
	ds_read_b128 v[248:251], v243 offset:96
	s_waitcnt lgkmcnt(2)
	v_mfma_f32_32x32x16_bf16 v[96:111], v[210:213], v[216:219], v[96:111]
	ds_read_b128 v[210:213], v205 offset:17504
	ds_read_b128 v[216:219], v206 offset:96
	s_waitcnt lgkmcnt(2)
	v_mfma_f32_32x32x16_bf16 v[112:127], v[244:247], v[248:251], v[112:127]
	ds_read_b128 v[244:247], v243 offset:17536
	ds_read_b128 v[248:251], v243 offset:128
	s_waitcnt lgkmcnt(2)
	v_mfma_f32_32x32x16_bf16 v[96:111], v[210:213], v[216:219], v[96:111]
	ds_read_b128 v[210:213], v205 offset:17536
	ds_read_b128 v[216:219], v206 offset:128
	s_waitcnt lgkmcnt(2)
	v_mfma_f32_32x32x16_bf16 v[112:127], v[244:247], v[248:251], v[112:127]
	ds_read_b128 v[244:247], v243 offset:17568
	ds_read_b128 v[248:251], v243 offset:160
	s_waitcnt lgkmcnt(2)
	v_mfma_f32_32x32x16_bf16 v[96:111], v[210:213], v[216:219], v[96:111]
	ds_read_b128 v[210:213], v205 offset:17568
	ds_read_b128 v[216:219], v206 offset:160
	s_waitcnt lgkmcnt(2)
	v_mfma_f32_32x32x16_bf16 v[112:127], v[244:247], v[248:251], v[112:127]
	ds_read_b128 v[244:247], v243 offset:17600
	ds_read_b128 v[248:251], v243 offset:192
	s_waitcnt lgkmcnt(2)
	v_mfma_f32_32x32x16_bf16 v[96:111], v[210:213], v[216:219], v[96:111]
	ds_read_b128 v[210:213], v205 offset:17600
	ds_read_b128 v[216:219], v206 offset:192
	s_waitcnt lgkmcnt(2)
	v_mfma_f32_32x32x16_bf16 v[112:127], v[244:247], v[248:251], v[112:127]
	ds_read_b128 v[244:247], v243 offset:17632
	ds_read_b128 v[248:251], v243 offset:224
	s_waitcnt lgkmcnt(2)
	v_mfma_f32_32x32x16_bf16 v[96:111], v[210:213], v[216:219], v[96:111]
	ds_read_b128 v[210:213], v205 offset:17632
	ds_read_b128 v[216:219], v206 offset:224
	s_waitcnt lgkmcnt(2)
	v_mfma_f32_32x32x16_bf16 v[112:127], v[244:247], v[248:251], v[112:127]
	s_waitcnt lgkmcnt(0)
	v_mfma_f32_32x32x16_bf16 v[96:111], v[210:213], v[216:219], v[96:111]
	ds_read_b32 v249, v224 offset:256
	ds_read_b32 v244, v169 offset:256
	ds_read_b32 v243, v225 offset:256
	ds_read_b32 v246, v226 offset:256
	ds_read_b32 v245, v227 offset:256
	ds_read_b32 v248, v228 offset:256
	ds_read_b32 v247, v229 offset:256
	ds_read_b32 v251, v230 offset:256
	ds_read_b32 v250, v231 offset:256
	s_waitcnt lgkmcnt(7)
	v_mul_f32_e32 v244, v192, v244
	v_mul_f32_e32 v244, v112, v244
	v_cndmask_b32_e64 v244, 0, v244, s[6:7]
	ds_read_b32 v112, v224 offset:260
	s_waitcnt lgkmcnt(7)
	v_mul_f32_e32 v243, v192, v243
	v_mul_f32_e32 v243, v113, v243
	v_cndmask_b32_e64 v243, 0, v243, s[8:9]
	ds_read_b32 v113, v224 offset:264
	s_waitcnt lgkmcnt(7)
	v_mul_f32_e32 v246, v192, v246
	v_mul_f32_e32 v246, v114, v246
	v_cndmask_b32_e64 v246, 0, v246, s[10:11]
	ds_read_b32 v114, v224 offset:268
	s_waitcnt lgkmcnt(7)
	v_mul_f32_e32 v245, v192, v245
	v_mul_f32_e32 v245, v115, v245
	v_cndmask_b32_e64 v245, 0, v245, s[12:13]
	ds_read_b32 v115, v224 offset:288
	s_waitcnt lgkmcnt(7)
	v_mul_f32_e32 v248, v192, v248
	v_mul_f32_e32 v248, v116, v248
	v_cndmask_b32_e64 v248, 0, v248, s[14:15]
	ds_read_b32 v116, v224 offset:292
	s_waitcnt lgkmcnt(7)
	v_mul_f32_e32 v247, v192, v247
	v_mul_f32_e32 v247, v117, v247
	v_cndmask_b32_e64 v247, 0, v247, s[16:17]
	ds_read_b32 v117, v224 offset:296
	s_waitcnt lgkmcnt(7)
	v_mul_f32_e32 v251, v192, v251
	v_mul_f32_e32 v251, v118, v251
	v_cndmask_b32_e64 v251, 0, v251, s[18:19]
	ds_read_b32 v118, v224 offset:300
	s_waitcnt lgkmcnt(7)
	v_mul_f32_e32 v250, v192, v250
	v_mul_f32_e32 v250, v119, v250
	v_cndmask_b32_e64 v250, 0, v250, s[20:21]
	ds_read_b32 v119, v224 offset:320
	ds_read_b32 v253, v232 offset:256
	ds_read_b32 v252, v233 offset:256
	ds_read_b32 v206, v234 offset:256
	ds_read_b32 v211, v235 offset:256
	ds_read_b32 v205, v236 offset:256
	ds_read_b32 v207, v237 offset:256
	ds_read_b32 v213, v238 offset:256
	ds_read_b32 v208, v239 offset:256
	s_waitcnt lgkmcnt(7)
	v_mul_f32_e32 v253, v192, v253
	v_mul_f32_e32 v253, v120, v253
	v_cndmask_b32_e64 v253, 0, v253, s[22:23]
	ds_read_b32 v120, v224 offset:324
	s_waitcnt lgkmcnt(7)
	v_mul_f32_e32 v252, v192, v252
	v_mul_f32_e32 v252, v121, v252
	v_cndmask_b32_e64 v252, 0, v252, s[24:25]
	ds_read_b32 v121, v224 offset:328
	s_waitcnt lgkmcnt(7)
	v_mul_f32_e32 v206, v192, v206
	v_mul_f32_e32 v206, v122, v206
	v_cndmask_b32_e64 v206, 0, v206, s[26:27]
	ds_read_b32 v122, v224 offset:332
	s_waitcnt lgkmcnt(7)
	v_mul_f32_e32 v211, v192, v211
	v_mul_f32_e32 v211, v123, v211
	v_cndmask_b32_e64 v211, 0, v211, s[28:29]
	ds_read_b32 v123, v224 offset:352
	s_waitcnt lgkmcnt(7)
	v_mul_f32_e32 v205, v192, v205
	v_mul_f32_e32 v205, v124, v205
	v_cndmask_b32_e64 v205, 0, v205, s[30:31]
	ds_read_b32 v124, v224 offset:356
	s_waitcnt lgkmcnt(7)
	v_mul_f32_e32 v207, v192, v207
	v_mul_f32_e32 v207, v125, v207
	v_cndmask_b32_e64 v207, 0, v207, s[34:35]
	ds_read_b32 v125, v224 offset:360
	s_waitcnt lgkmcnt(7)
	v_mul_f32_e32 v213, v192, v213
	v_mul_f32_e32 v213, v126, v213
	v_cndmask_b32_e64 v213, 0, v213, s[36:37]
	ds_read_b32 v126, v224 offset:364
	s_waitcnt lgkmcnt(7)
	v_mul_f32_e32 v208, v192, v208
	v_mul_f32_e32 v208, v127, v208
	v_cndmask_b32_e64 v208, 0, v208, s[38:39]

; DI int crow(int r, int hi) { return (r & 3) + 8 * (r >> 2) + 4 * hi; }
; template <bool ML>
; DI void scan_block(const Params& p, int sitem, char* smem) {
;     ...
; #pragma unroll
;         for (int r = 0; r < 16; ++r) {
;           const int sl = crow(r, hi);
;           const bool valid = dir == 0 ? sl <= l32 : sl >= l32;
;           float w1;
;           if (ML) w1 = __expf(sB1 + wsm[96 + sl]);
;           else w1 = sB1 * wsm[96 + sl];
;           sa[r] = valid ? (sa[r] + sb_[r]) * w1 : 0.f;
;         }
.LBB0_1502:
	ds_read_b128 v[244:247], v190 offset:17408
	ds_read_b128 v[248:251], v190
	ds_read_b128 v[210:213], v190 offset:17440
	ds_read_b128 v[216:219], v190 offset:32
	s_waitcnt lgkmcnt(2)
	v_mfma_f32_32x32x16_bf16 v[112:127], v[244:247], v[248:251], v[112:127]
	ds_read_b128 v[244:247], v190 offset:17472
	ds_read_b128 v[248:251], v190 offset:64
	s_waitcnt lgkmcnt(2)
	v_mfma_f32_32x32x16_bf16 v[96:111], v[210:213], v[216:219], v[96:111]
	ds_read_b128 v[210:213], v190 offset:17504
	ds_read_b128 v[216:219], v190 offset:96
	s_waitcnt lgkmcnt(2)
	v_mfma_f32_32x32x16_bf16 v[112:127], v[244:247], v[248:251], v[112:127]
	ds_read_b128 v[244:247], v190 offset:17536
	ds_read_b128 v[248:251], v190 offset:128
	s_waitcnt lgkmcnt(2)
	v_mfma_f32_32x32x16_bf16 v[96:111], v[210:213], v[216:219], v[96:111]
	ds_read_b128 v[210:213], v190 offset:17568
	ds_read_b128 v[216:219], v190 offset:160
	s_waitcnt lgkmcnt(2)
	v_mfma_f32_32x32x16_bf16 v[112:127], v[244:247], v[248:251], v[112:127]
	ds_read_b128 v[244:247], v190 offset:17600
	ds_read_b128 v[248:251], v190 offset:192
	s_waitcnt lgkmcnt(2)
	v_mfma_f32_32x32x16_bf16 v[96:111], v[210:213], v[216:219], v[96:111]
	ds_read_b128 v[210:213], v190 offset:17632
	ds_read_b128 v[216:219], v190 offset:224
	s_waitcnt lgkmcnt(2)
	v_mfma_f32_32x32x16_bf16 v[112:127], v[244:247], v[248:251], v[112:127]
	s_waitcnt lgkmcnt(0)
	v_mfma_f32_32x32x16_bf16 v[96:111], v[210:213], v[216:219], v[96:111]
	ds_read_b32 v244, v169 offset:384
	ds_read_b32 v245, v225 offset:384
	ds_read_b32 v246, v226 offset:384
	ds_read_b32 v247, v227 offset:384
	ds_read_b32 v248, v228 offset:384
	ds_read_b32 v249, v229 offset:384
	ds_read_b32 v250, v230 offset:384
	ds_read_b32 v251, v231 offset:384
	s_nop 6
	v_add_f32_e32 v96, v112, v96
	s_waitcnt lgkmcnt(7)
	v_mul_f32_e32 v244, v242, v244
	v_mul_f32_e32 v193, v96, v244
	v_cndmask_b32_e64 v193, 0, v193, s[6:7]
	s_nop 3
	v_add_f32_e32 v96, v113, v97
	s_waitcnt lgkmcnt(6)
	v_mul_f32_e32 v245, v242, v245
	v_mul_f32_e32 v190, v96, v245
	v_cndmask_b32_e64 v190, 0, v190, s[8:9]
	v_add_f32_e32 v97, v114, v98
	s_waitcnt lgkmcnt(5)
	v_mul_f32_e32 v246, v242, v246
	v_mul_f32_e32 v97, v97, v246
	v_cndmask_b32_e64 v97, 0, v97, s[10:11]
	v_add_f32_e32 v96, v115, v99
	s_waitcnt lgkmcnt(4)
	v_mul_f32_e32 v247, v242, v247
	v_mul_f32_e32 v96, v96, v247
	v_cndmask_b32_e64 v96, 0, v96, s[12:13]
	v_add_f32_e32 v99, v116, v100
	s_waitcnt lgkmcnt(3)
	v_mul_f32_e32 v248, v242, v248
	v_mul_f32_e32 v99, v99, v248
	v_cndmask_b32_e64 v99, 0, v99, s[14:15]
	v_add_f32_e32 v98, v117, v101
	s_waitcnt lgkmcnt(2)
	v_mul_f32_e32 v249, v242, v249
	v_mul_f32_e32 v98, v98, v249
	v_cndmask_b32_e64 v98, 0, v98, s[16:17]
	v_add_f32_e32 v101, v118, v102
	s_waitcnt lgkmcnt(1)
	v_mul_f32_e32 v250, v242, v250
	v_mul_f32_e32 v101, v101, v250
	v_cndmask_b32_e64 v101, 0, v101, s[18:19]
	v_add_f32_e32 v100, v119, v103
	s_waitcnt lgkmcnt(0)
	v_mul_f32_e32 v251, v242, v251
	v_mul_f32_e32 v100, v100, v251
	v_cndmask_b32_e64 v100, 0, v100, s[20:21]
	ds_read_b32 v252, v232 offset:384
	ds_read_b32 v253, v233 offset:384
	ds_read_b32 v205, v234 offset:384
	ds_read_b32 v206, v235 offset:384
	ds_read_b32 v207, v236 offset:384
	ds_read_b32 v208, v237 offset:384
	ds_read_b32 v210, v238 offset:384
	ds_read_b32 v211, v239 offset:384
	v_add_f32_e32 v103, v120, v104
	s_waitcnt lgkmcnt(7)
	v_mul_f32_e32 v252, v242, v252
	v_mul_f32_e32 v103, v103, v252
	v_cndmask_b32_e64 v103, 0, v103, s[22:23]
	v_add_f32_e32 v102, v121, v105
	s_waitcnt lgkmcnt(6)
	v_mul_f32_e32 v253, v242, v253
	v_mul_f32_e32 v102, v102, v253
	v_cndmask_b32_e64 v102, 0, v102, s[24:25]
	v_add_f32_e32 v105, v122, v106
	s_waitcnt lgkmcnt(5)
	v_mul_f32_e32 v205, v242, v205
	v_mul_f32_e32 v105, v105, v205
	v_cndmask_b32_e64 v105, 0, v105, s[26:27]
	v_add_f32_e32 v104, v123, v107
	s_waitcnt lgkmcnt(4)
	v_mul_f32_e32 v206, v242, v206
	v_mul_f32_e32 v104, v104, v206
	v_cndmask_b32_e64 v104, 0, v104, s[28:29]
	v_add_f32_e32 v107, v124, v108
	s_waitcnt lgkmcnt(3)
	v_mul_f32_e32 v207, v242, v207
	v_mul_f32_e32 v107, v107, v207
	v_cndmask_b32_e64 v107, 0, v107, s[30:31]
	v_add_f32_e32 v106, v125, v109
	s_waitcnt lgkmcnt(2)
	v_mul_f32_e32 v208, v242, v208
	v_mul_f32_e32 v106, v106, v208
	v_cndmask_b32_e64 v106, 0, v106, s[34:35]
	v_add_f32_e32 v109, v126, v110
	s_waitcnt lgkmcnt(1)
	v_mul_f32_e32 v210, v242, v210
	v_mul_f32_e32 v109, v109, v210
	v_cndmask_b32_e64 v109, 0, v109, s[36:37]
	v_add_f32_e32 v108, v127, v111
	s_waitcnt lgkmcnt(0)
	v_mul_f32_e32 v211, v242, v211
	v_mul_f32_e32 v108, v108, v211
	v_cndmask_b32_e64 v108, 0, v108, s[38:39]
